# grid barrier: waiting workgroups poll the release word every ~0.25 us instead of back-to-back
# speedup vs baseline: 1.0053x; 1.0053x over previous
.LBB0_2178:
	s_and_b32 s2, s33, 0xff
	s_mov_b64 s[42:43], -1
	s_cmp_lg_u32 s2, 0
	s_mov_b64 s[46:47], -1
	s_sleep 8
	s_cbranch_scc0 .LBB0_2181
	s_and_b64 vcc, exec, s[46:47]
	s_cbranch_vccz .LBB0_2177
